# combination plus hand-written short-conv rows (tap weights in registers, next row's lines requested early)
# speedup vs baseline: 1.0200x; 1.0003x over previous
.LBB0_351:
	s_mul_i32 s0, s43, 0x2100
	s_add_i32 s78, s0, 0
	s_mov_b64 s[12:13], -1
	s_and_b64 vcc, exec, s[66:67]
	s_cbranch_vccz .LBB0_388
	s_add_i32 s0, s8, s6
	s_movk_i32 s1, 0x3000
	s_cmp_ge_i32 s0, s1
	s_cbranch_scc1 .LcvA_end
	s_load_dwordx4 s[36:39], s[58:59], 0x90
	s_and_b64 s[12:13], s[62:63], exec
	s_cselect_b32 s3, 0x3000, 0
	s_cselect_b32 s5, 0x1000, 0
	v_lshlrev_b32_e32 v0, 5, v168
	s_waitcnt lgkmcnt(0)
	s_add_u32 s36, s36, s3
	s_addc_u32 s37, s37, 0
	s_add_u32 s38, s38, s5
	s_addc_u32 s39, s39, 0
	s_add_u32 s12, s36, 0x0
	s_addc_u32 s13, s37, 0
	global_load_dwordx4 v[170:173], v0, s[12:13]
	global_load_dwordx4 v[174:177], v0, s[12:13] offset:16
	s_add_u32 s12, s36, 0x800
	s_addc_u32 s13, s37, 0
	global_load_dwordx4 v[178:181], v0, s[12:13]
	global_load_dwordx4 v[182:185], v0, s[12:13] offset:16
	s_add_u32 s12, s36, 0x1000
	s_addc_u32 s13, s37, 0
	global_load_dwordx4 v[186:189], v0, s[12:13]
	global_load_dwordx4 v[190:193], v0, s[12:13] offset:16
	s_add_u32 s12, s36, 0x1800
	s_addc_u32 s13, s37, 0
	global_load_dwordx4 v[194:197], v0, s[12:13]
	global_load_dwordx4 v[198:201], v0, s[12:13] offset:16
	s_add_u32 s12, s36, 0x2000
	s_addc_u32 s13, s37, 0
	global_load_dwordx4 v[202:205], v0, s[12:13]
	global_load_dwordx4 v[206:209], v0, s[12:13] offset:16
	s_add_u32 s12, s36, 0x2800
	s_addc_u32 s13, s37, 0
	global_load_dwordx4 v[210:213], v0, s[12:13]
	global_load_dwordx4 v[214:217], v0, s[12:13] offset:16
	global_load_dwordx4 v[218:221], v0, s[38:39]
	global_load_dwordx4 v[222:225], v0, s[38:39] offset:16
	global_load_dwordx4 v[226:229], v0, s[38:39] offset:2048
	global_load_dwordx4 v[230:233], v0, s[38:39] offset:2064
	s_ashr_i32 s3, s0, 31
	s_lshl_b32 s12, s0, 13
	s_add_u32 s66, s56, 0x1a001000
	s_addc_u32 s67, s57, 0
	s_add_u32 s66, s66, s12
	s_addc_u32 s67, s67, 0
	s_lshl_b32 s12, s0, 12
	s_add_u32 s68, s56, 0x15800800
	s_addc_u32 s69, s57, 0
	s_add_u32 s68, s68, s12
	s_addc_u32 s69, s69, 0
	v_lshlrev_b32_e32 v0, 4, v168
	v_mov_b32_e32 v1, 0
	v_lshl_add_u64 v[2:3], s[66:67], 0, v[0:1]
	v_lshl_add_u64 v[6:7], s[68:69], 0, v[0:1]
	s_lshl_b32 s12, s4, 13
	s_mov_b32 s13, 0
	s_lshl_b32 s72, s4, 12
	s_mov_b32 s73, 0
	s_mov_b32 s66, 0xffffe000
	s_mov_b32 s67, -1
	s_mov_b32 s68, 0x2000
	s_mov_b32 s69, 0
.LcvA_row:
	s_cmpk_lt_i32 s0, 0x1000
	s_cselect_b32 s3, 0xff, 63
	s_and_b32 s5, s3, s0
	global_load_dwordx4 v[26:29], v[2:3], off
	global_load_dwordx4 v[34:37], v[2:3], off offset:2048
	global_load_dwordx4 v[18:21], v[2:3], off offset:-2048
	global_load_dwordx4 v[30:33], v[2:3], off offset:1024
	global_load_dwordx4 v[38:41], v[2:3], off offset:3072
	global_load_dwordx4 v[22:25], v[2:3], off offset:-1024
	s_cmp_eq_u32 s5, 0
	s_cbranch_scc1 .LcvA_noprev
	v_lshl_add_u64 v[8:9], v[2:3], 0, s[66:67]
	global_load_dwordx4 v[42:45], v[8:9], off
	global_load_dwordx4 v[50:53], v[8:9], off offset:2048
	global_load_dwordx4 v[46:49], v[8:9], off offset:1024
	global_load_dwordx4 v[54:57], v[8:9], off offset:3072
	s_branch .LcvA_prevdone
.LcvA_noprev:
	v_mov_b32_e32 v42, 0
	v_mov_b32_e32 v43, 0
	v_mov_b32_e32 v44, 0
	v_mov_b32_e32 v45, 0
	v_mov_b32_e32 v46, 0
	v_mov_b32_e32 v47, 0
	v_mov_b32_e32 v48, 0
	v_mov_b32_e32 v49, 0
	v_mov_b32_e32 v50, 0
	v_mov_b32_e32 v51, 0
	v_mov_b32_e32 v52, 0
	v_mov_b32_e32 v53, 0
	v_mov_b32_e32 v54, 0
	v_mov_b32_e32 v55, 0
	v_mov_b32_e32 v56, 0
	v_mov_b32_e32 v57, 0
.LcvA_prevdone:
	s_cmp_eq_u32 s5, s3
	s_cbranch_scc1 .LcvA_nonext
	v_lshl_add_u64 v[8:9], v[2:3], 0, s[68:69]
	global_load_dwordx4 v[58:61], v[8:9], off
	global_load_dwordx4 v[66:69], v[8:9], off offset:2048
	global_load_dwordx4 v[62:65], v[8:9], off offset:1024
	global_load_dwordx4 v[70:73], v[8:9], off offset:3072
	s_branch .LcvA_nextdone
.LcvA_nonext:
	v_mov_b32_e32 v58, 0
	v_mov_b32_e32 v59, 0
	v_mov_b32_e32 v60, 0
	v_mov_b32_e32 v61, 0
	v_mov_b32_e32 v62, 0
	v_mov_b32_e32 v63, 0
	v_mov_b32_e32 v64, 0
	v_mov_b32_e32 v65, 0
	v_mov_b32_e32 v66, 0
	v_mov_b32_e32 v67, 0
	v_mov_b32_e32 v68, 0
	v_mov_b32_e32 v69, 0
	v_mov_b32_e32 v70, 0
	v_mov_b32_e32 v71, 0
	v_mov_b32_e32 v72, 0
	v_mov_b32_e32 v73, 0
.LcvA_nextdone:
	s_add_i32 s3, s0, s4
	s_cmp_ge_i32 s3, s1
	s_cbranch_scc1 .LcvA_nopf
	v_lshl_add_u64 v[8:9], v[2:3], 0, s[12:13]
	global_load_dwordx4 v[98:101], v[8:9], off offset:-2048
	global_load_dwordx4 v[98:101], v[8:9], off offset:-1024
	global_load_dwordx4 v[98:101], v[8:9], off
	global_load_dwordx4 v[98:101], v[8:9], off offset:1024
	global_load_dwordx4 v[98:101], v[8:9], off offset:2048
	global_load_dwordx4 v[98:101], v[8:9], off offset:3072
	s_waitcnt vmcnt(6)
	s_branch .LcvA_pfdone

.LcvA_pfdone:
	v_lshlrev_b32_e32 v74, 16, v26
	v_and_b32_e32 v75, 0xffff0000, v26
	v_lshlrev_b32_e32 v76, 16, v34
	v_and_b32_e32 v77, 0xffff0000, v34
	v_pk_mul_f32 v[78:79], v[74:75], v[76:77]
	v_lshlrev_b32_e32 v74, 16, v42
	v_and_b32_e32 v75, 0xffff0000, v42
	v_lshlrev_b32_e32 v76, 16, v50
	v_and_b32_e32 v77, 0xffff0000, v50
	v_pk_mul_f32 v[80:81], v[74:75], v[76:77]
	v_lshlrev_b32_e32 v74, 16, v58
	v_and_b32_e32 v75, 0xffff0000, v58
	v_lshlrev_b32_e32 v76, 16, v66
	v_and_b32_e32 v77, 0xffff0000, v66
	v_pk_mul_f32 v[82:83], v[74:75], v[76:77]
	v_pk_mul_f32 v[84:85], v[78:79], v[186:187]
	v_pk_fma_f32 v[84:85], v[80:81], v[170:171], v[84:85]
	v_pk_fma_f32 v[84:85], v[82:83], v[202:203], v[84:85]
	v_pk_add_f32 v[84:85], v[218:219], v[84:85]
	v_lshlrev_b32_e32 v74, 16, v18
	v_and_b32_e32 v75, 0xffff0000, v18
	v_pk_mul_f32 v[84:85], v[84:85], v[74:75]
	v_cvt_pk_bf16_f32 v90, v84, v85
	v_lshlrev_b32_e32 v74, 16, v27
	v_and_b32_e32 v75, 0xffff0000, v27
	v_lshlrev_b32_e32 v76, 16, v35
	v_and_b32_e32 v77, 0xffff0000, v35
	v_pk_mul_f32 v[78:79], v[74:75], v[76:77]
	v_lshlrev_b32_e32 v74, 16, v43
	v_and_b32_e32 v75, 0xffff0000, v43
	v_lshlrev_b32_e32 v76, 16, v51
	v_and_b32_e32 v77, 0xffff0000, v51
	v_pk_mul_f32 v[80:81], v[74:75], v[76:77]
	v_lshlrev_b32_e32 v74, 16, v59
	v_and_b32_e32 v75, 0xffff0000, v59
	v_lshlrev_b32_e32 v76, 16, v67
	v_and_b32_e32 v77, 0xffff0000, v67
	v_pk_mul_f32 v[82:83], v[74:75], v[76:77]
	v_pk_mul_f32 v[84:85], v[78:79], v[188:189]
	v_pk_fma_f32 v[84:85], v[80:81], v[172:173], v[84:85]
	v_pk_fma_f32 v[84:85], v[82:83], v[204:205], v[84:85]
	v_pk_add_f32 v[84:85], v[220:221], v[84:85]
	v_lshlrev_b32_e32 v74, 16, v19
	v_and_b32_e32 v75, 0xffff0000, v19
	v_pk_mul_f32 v[84:85], v[84:85], v[74:75]
	v_cvt_pk_bf16_f32 v91, v84, v85
	v_lshlrev_b32_e32 v74, 16, v28
	v_and_b32_e32 v75, 0xffff0000, v28
	v_lshlrev_b32_e32 v76, 16, v36
	v_and_b32_e32 v77, 0xffff0000, v36
	v_pk_mul_f32 v[78:79], v[74:75], v[76:77]
	v_lshlrev_b32_e32 v74, 16, v44
	v_and_b32_e32 v75, 0xffff0000, v44
	v_lshlrev_b32_e32 v76, 16, v52
	v_and_b32_e32 v77, 0xffff0000, v52
	v_pk_mul_f32 v[80:81], v[74:75], v[76:77]
	v_lshlrev_b32_e32 v74, 16, v60
	v_and_b32_e32 v75, 0xffff0000, v60
	v_lshlrev_b32_e32 v76, 16, v68
	v_and_b32_e32 v77, 0xffff0000, v68
	v_pk_mul_f32 v[82:83], v[74:75], v[76:77]
	v_pk_mul_f32 v[84:85], v[78:79], v[190:191]
	v_pk_fma_f32 v[84:85], v[80:81], v[174:175], v[84:85]
	v_pk_fma_f32 v[84:85], v[82:83], v[206:207], v[84:85]
	v_pk_add_f32 v[84:85], v[222:223], v[84:85]
	v_lshlrev_b32_e32 v74, 16, v20
	v_and_b32_e32 v75, 0xffff0000, v20
	v_pk_mul_f32 v[84:85], v[84:85], v[74:75]
	v_cvt_pk_bf16_f32 v92, v84, v85
	v_lshlrev_b32_e32 v74, 16, v29
	v_and_b32_e32 v75, 0xffff0000, v29
	v_lshlrev_b32_e32 v76, 16, v37
	v_and_b32_e32 v77, 0xffff0000, v37
	v_pk_mul_f32 v[78:79], v[74:75], v[76:77]
	v_lshlrev_b32_e32 v74, 16, v45
	v_and_b32_e32 v75, 0xffff0000, v45
	v_lshlrev_b32_e32 v76, 16, v53
	v_and_b32_e32 v77, 0xffff0000, v53
	v_pk_mul_f32 v[80:81], v[74:75], v[76:77]
	v_lshlrev_b32_e32 v74, 16, v61
	v_and_b32_e32 v75, 0xffff0000, v61
	v_lshlrev_b32_e32 v76, 16, v69
	v_and_b32_e32 v77, 0xffff0000, v69
	v_pk_mul_f32 v[82:83], v[74:75], v[76:77]
	v_pk_mul_f32 v[84:85], v[78:79], v[192:193]
	v_pk_fma_f32 v[84:85], v[80:81], v[176:177], v[84:85]
	v_pk_fma_f32 v[84:85], v[82:83], v[208:209], v[84:85]
	v_pk_add_f32 v[84:85], v[224:225], v[84:85]
	v_lshlrev_b32_e32 v74, 16, v21
	v_and_b32_e32 v75, 0xffff0000, v21
	v_pk_mul_f32 v[84:85], v[84:85], v[74:75]
	v_cvt_pk_bf16_f32 v93, v84, v85
	v_lshlrev_b32_e32 v74, 16, v30
	v_and_b32_e32 v75, 0xffff0000, v30
	v_lshlrev_b32_e32 v76, 16, v38
	v_and_b32_e32 v77, 0xffff0000, v38
	v_pk_mul_f32 v[78:79], v[74:75], v[76:77]
	v_lshlrev_b32_e32 v74, 16, v46
	v_and_b32_e32 v75, 0xffff0000, v46
	v_lshlrev_b32_e32 v76, 16, v54
	v_and_b32_e32 v77, 0xffff0000, v54
	v_pk_mul_f32 v[80:81], v[74:75], v[76:77]
	v_lshlrev_b32_e32 v74, 16, v62
	v_and_b32_e32 v75, 0xffff0000, v62
	v_lshlrev_b32_e32 v76, 16, v70
	v_and_b32_e32 v77, 0xffff0000, v70
	v_pk_mul_f32 v[82:83], v[74:75], v[76:77]
	v_pk_mul_f32 v[84:85], v[78:79], v[194:195]
	v_pk_fma_f32 v[84:85], v[80:81], v[178:179], v[84:85]
	v_pk_fma_f32 v[84:85], v[82:83], v[210:211], v[84:85]
	v_pk_add_f32 v[84:85], v[226:227], v[84:85]
	v_lshlrev_b32_e32 v74, 16, v22
	v_and_b32_e32 v75, 0xffff0000, v22
	v_pk_mul_f32 v[84:85], v[84:85], v[74:75]
	v_cvt_pk_bf16_f32 v94, v84, v85
	v_lshlrev_b32_e32 v74, 16, v31
	v_and_b32_e32 v75, 0xffff0000, v31
	v_lshlrev_b32_e32 v76, 16, v39
	v_and_b32_e32 v77, 0xffff0000, v39
	v_pk_mul_f32 v[78:79], v[74:75], v[76:77]
	v_lshlrev_b32_e32 v74, 16, v47
	v_and_b32_e32 v75, 0xffff0000, v47
	v_lshlrev_b32_e32 v76, 16, v55
	v_and_b32_e32 v77, 0xffff0000, v55
	v_pk_mul_f32 v[80:81], v[74:75], v[76:77]
	v_lshlrev_b32_e32 v74, 16, v63
	v_and_b32_e32 v75, 0xffff0000, v63
	v_lshlrev_b32_e32 v76, 16, v71
	v_and_b32_e32 v77, 0xffff0000, v71
	v_pk_mul_f32 v[82:83], v[74:75], v[76:77]
	v_pk_mul_f32 v[84:85], v[78:79], v[196:197]
	v_pk_fma_f32 v[84:85], v[80:81], v[180:181], v[84:85]
	v_pk_fma_f32 v[84:85], v[82:83], v[212:213], v[84:85]
	v_pk_add_f32 v[84:85], v[228:229], v[84:85]
	v_lshlrev_b32_e32 v74, 16, v23
	v_and_b32_e32 v75, 0xffff0000, v23
	v_pk_mul_f32 v[84:85], v[84:85], v[74:75]
	v_cvt_pk_bf16_f32 v95, v84, v85
	v_lshlrev_b32_e32 v74, 16, v32
	v_and_b32_e32 v75, 0xffff0000, v32
	v_lshlrev_b32_e32 v76, 16, v40
	v_and_b32_e32 v77, 0xffff0000, v40
	v_pk_mul_f32 v[78:79], v[74:75], v[76:77]
	v_lshlrev_b32_e32 v74, 16, v48
	v_and_b32_e32 v75, 0xffff0000, v48
	v_lshlrev_b32_e32 v76, 16, v56
	v_and_b32_e32 v77, 0xffff0000, v56
	v_pk_mul_f32 v[80:81], v[74:75], v[76:77]
	v_lshlrev_b32_e32 v74, 16, v64
	v_and_b32_e32 v75, 0xffff0000, v64
	v_lshlrev_b32_e32 v76, 16, v72
	v_and_b32_e32 v77, 0xffff0000, v72
	v_pk_mul_f32 v[82:83], v[74:75], v[76:77]
	v_pk_mul_f32 v[84:85], v[78:79], v[198:199]
	v_pk_fma_f32 v[84:85], v[80:81], v[182:183], v[84:85]
	v_pk_fma_f32 v[84:85], v[82:83], v[214:215], v[84:85]
	v_pk_add_f32 v[84:85], v[230:231], v[84:85]
	v_lshlrev_b32_e32 v74, 16, v24
	v_and_b32_e32 v75, 0xffff0000, v24
	v_pk_mul_f32 v[84:85], v[84:85], v[74:75]
	v_cvt_pk_bf16_f32 v96, v84, v85
	v_lshlrev_b32_e32 v74, 16, v33
	v_and_b32_e32 v75, 0xffff0000, v33
	v_lshlrev_b32_e32 v76, 16, v41
	v_and_b32_e32 v77, 0xffff0000, v41
	v_pk_mul_f32 v[78:79], v[74:75], v[76:77]
	v_lshlrev_b32_e32 v74, 16, v49
	v_and_b32_e32 v75, 0xffff0000, v49
	v_lshlrev_b32_e32 v76, 16, v57
	v_and_b32_e32 v77, 0xffff0000, v57
	v_pk_mul_f32 v[80:81], v[74:75], v[76:77]
	v_lshlrev_b32_e32 v74, 16, v65
	v_and_b32_e32 v75, 0xffff0000, v65
	v_lshlrev_b32_e32 v76, 16, v73
	v_and_b32_e32 v77, 0xffff0000, v73
	v_pk_mul_f32 v[82:83], v[74:75], v[76:77]
	v_pk_mul_f32 v[84:85], v[78:79], v[200:201]
	v_pk_fma_f32 v[84:85], v[80:81], v[184:185], v[84:85]
	v_pk_fma_f32 v[84:85], v[82:83], v[216:217], v[84:85]
	v_pk_add_f32 v[84:85], v[232:233], v[84:85]
	v_lshlrev_b32_e32 v74, 16, v25
	v_and_b32_e32 v75, 0xffff0000, v25
	v_pk_mul_f32 v[84:85], v[84:85], v[74:75]
	v_cvt_pk_bf16_f32 v97, v84, v85
	global_store_dwordx4 v[6:7], v[90:93], off
	global_store_dwordx4 v[6:7], v[94:97], off offset:1024
	v_lshl_add_u64 v[2:3], v[2:3], 0, s[12:13]
	v_lshl_add_u64 v[6:7], v[6:7], 0, s[72:73]
	s_add_i32 s0, s0, s4
	s_cmp_lt_i32 s0, s1
	s_cbranch_scc1 .LcvA_row
.LcvA_end:
.LBB0_365:
	s_cmpk_lt_i32 s6, 0x1000
	s_cselect_b64 s[0:1], -1, 0
	s_and_b64 s[0:1], s[10:11], s[0:1]
	s_andn2_b64 vcc, exec, s[0:1]
	s_mov_b64 s[70:71], 0x20000000
	s_cbranch_vccnz .LBB0_368
	s_load_dwordx2 s[0:1], s[58:59], 0x80
	s_and_b64 s[10:11], s[62:63], exec
	s_cselect_b32 s3, 0x1000, 0
	v_lshlrev_b32_e32 v0, 5, v168
	v_mov_b32_e32 v1, v4
	s_waitcnt lgkmcnt(0)
	s_add_u32 s0, s0, s3
	s_addc_u32 s1, s1, 0
	v_lshl_add_u64 v[18:19], s[0:1], 0, v[0:1]
	s_add_i32 s0, s6, 0x3000
	s_ashr_i32 s1, s0, 31
	s_lshl_b64 s[0:1], s[0:1], 12
	s_ashr_i32 s7, s6, 31
	v_or_b32_e32 v20, s0, v0
	v_mov_b32_e32 v21, s1
	s_lshl_b64 s[0:1], s[6:7], 11
	v_lshlrev_b32_e32 v1, 4, v168
	v_or_b32_e32 v22, s0, v1
	v_mov_b32_e32 v23, s1
	s_lshl_b64 s[0:1], s[6:7], 12
	s_ashr_i32 s5, s4, 31
	v_or_b32_e32 v24, s0, v0
	v_mov_b32_e32 v25, s1
	s_lshl_b64 s[0:1], s[6:7], 13
	s_lshl_b64 s[10:11], s[4:5], 12
	s_lshl_b64 s[12:13], s[4:5], 11
	v_or_b32_e32 v26, s0, v1
	v_mov_b32_e32 v27, s1
	s_lshl_b64 s[66:67], s[4:5], 13
	s_mov_b32 s1, s6
	s_mov_b32 s0, 0x18800000
	s_mov_b64 s[18:19], 0x20000800

.LBB0_388:
	s_and_b64 vcc, exec, s[12:13]
	s_cbranch_vccz .LBB0_441
	s_mov_b32 s0, s6
	s_mov_b32 s1, s8
	s_cmp_ge_i32 s0, s1
	s_cbranch_scc1 .LcvB_end
	s_load_dwordx4 s[36:39], s[58:59], 0x90
	s_and_b64 s[12:13], s[62:63], exec
	s_cselect_b32 s3, 0x3000, 0
	s_cselect_b32 s5, 0x1000, 0
	v_lshlrev_b32_e32 v0, 5, v168
	s_waitcnt lgkmcnt(0)
	s_add_u32 s36, s36, s3
	s_addc_u32 s37, s37, 0
	s_add_u32 s38, s38, s5
	s_addc_u32 s39, s39, 0
	s_add_u32 s12, s36, 0x0
	s_addc_u32 s13, s37, 0
	global_load_dwordx4 v[170:173], v0, s[12:13]
	global_load_dwordx4 v[174:177], v0, s[12:13] offset:16
	s_add_u32 s12, s36, 0x800
	s_addc_u32 s13, s37, 0
	global_load_dwordx4 v[178:181], v0, s[12:13]
	global_load_dwordx4 v[182:185], v0, s[12:13] offset:16
	s_add_u32 s12, s36, 0x1000
	s_addc_u32 s13, s37, 0
	global_load_dwordx4 v[186:189], v0, s[12:13]
	global_load_dwordx4 v[190:193], v0, s[12:13] offset:16
	s_add_u32 s12, s36, 0x1800
	s_addc_u32 s13, s37, 0
	global_load_dwordx4 v[194:197], v0, s[12:13]
	global_load_dwordx4 v[198:201], v0, s[12:13] offset:16
	s_add_u32 s12, s36, 0x2000
	s_addc_u32 s13, s37, 0
	global_load_dwordx4 v[202:205], v0, s[12:13]
	global_load_dwordx4 v[206:209], v0, s[12:13] offset:16
	s_add_u32 s12, s36, 0x2800
	s_addc_u32 s13, s37, 0
	global_load_dwordx4 v[210:213], v0, s[12:13]
	global_load_dwordx4 v[214:217], v0, s[12:13] offset:16
	global_load_dwordx4 v[218:221], v0, s[38:39]
	global_load_dwordx4 v[222:225], v0, s[38:39] offset:16
	global_load_dwordx4 v[226:229], v0, s[38:39] offset:2048
	global_load_dwordx4 v[230:233], v0, s[38:39] offset:2064
	s_ashr_i32 s3, s0, 31
	s_lshl_b32 s12, s0, 13
	s_add_u32 s66, s56, 0x1a001000
	s_addc_u32 s67, s57, 0
	s_add_u32 s66, s66, s12
	s_addc_u32 s67, s67, 0
	s_lshl_b32 s12, s0, 12
	s_add_u32 s68, s56, 0x15800800
	s_addc_u32 s69, s57, 0
	s_add_u32 s68, s68, s12
	s_addc_u32 s69, s69, 0
	v_lshlrev_b32_e32 v0, 4, v168
	v_mov_b32_e32 v1, 0
	v_lshl_add_u64 v[2:3], s[66:67], 0, v[0:1]
	v_lshl_add_u64 v[6:7], s[68:69], 0, v[0:1]
	s_lshl_b32 s12, s4, 13
	s_mov_b32 s13, 0
	s_lshl_b32 s72, s4, 12
	s_mov_b32 s73, 0
	s_mov_b32 s66, 0xffffe000
	s_mov_b32 s67, -1
	s_mov_b32 s68, 0x2000
	s_mov_b32 s69, 0

.LcvB_end:
.LBB0_402:
	v_readlane_b32 s0, v247, 9
	v_readlane_b32 s1, v247, 10
	v_readlane_b32 s72, v247, 5
	v_readlane_b32 s68, v247, 7
	s_and_b64 vcc, exec, s[0:1]
	v_readlane_b32 s73, v247, 6
	v_readlane_b32 s69, v247, 8
	s_cbranch_vccz .LBB0_441
	s_branch .LBB0_441
	s_add_i32 s1, s6, 0x1000
	s_add_u32 s3, s56, 0x9c00000
	s_addc_u32 s5, s57, 0
	s_add_u32 s7, s56, 0x4400000
	s_addc_u32 s12, s57, 0
	s_add_u32 s13, s56, 0x3400000
	s_addc_u32 s15, s57, 0
	s_add_u32 s18, s56, 0x3000000
	v_lshrrev_b32_e32 v1, 5, v168
	v_and_b32_e32 v0, 31, v241
	s_addc_u32 s19, s57, 0
	v_lshlrev_b32_e32 v2, 2, v0
	v_mul_u32_u24_e32 v3, 0x84, v1
	s_add_u32 s25, s56, 0x1000000
	v_add3_u32 v3, s78, v2, v3
	v_lshlrev_b32_e32 v2, 3, v168
	s_addc_u32 s36, s57, 0
	v_lshrrev_b32_e32 v5, 3, v168
	v_and_b32_e32 v2, 56, v2
	s_lshl_b32 s0, s6, 5
	v_mul_u32_u24_e32 v6, 0x84, v2
	v_lshlrev_b32_e32 v7, 2, v5
	s_add_i32 s37, s0, 0x20000
	s_lshl_b32 s0, s6, 1
	v_add3_u32 v10, s78, v6, v7
	v_or_b32_e32 v11, 8, v5
	v_or_b32_e32 v12, 16, v5
	v_or_b32_e32 v13, 24, v5
	s_lshl_b32 s38, s4, 5
	s_add_i32 s39, s0, 0x2000
	s_lshl_b32 s40, s4, 1
	s_branch .LBB0_406
